# GEMM K-loop: duplicate lgkmcnt(0) waits removed (12 per tile iteration pair)
# speedup vs baseline: 1.0081x; 1.0015x over previous
; #define PG8_STAGE(bufoff, gbase, voff) do { _Pragma("unroll") for (int _i = 0; _i < 2; ++_i) \
;         __builtin_amdgcn_global_load_lds((const unsigned*)((const char*)(gbase) + (voff)[_i]), (PG8_LAS unsigned*)(lds + (bufoff) + ldsw + _i * 8192), 16, 0, 0); } while (0)
; #define PG8_LDA(dst, b, h) do { _Pragma("unroll") for (int m = 0; m < 4; ++m) _Pragma("unroll") for (int k = 0; k < 2; ++k) dst[m][k] = *(const PG8_LAS bf16x8*)(lds + PG8_SA(b, h) + aoff + m * 2048 + k * 1024); } while (0)
; #define PG8_LDB(dst, b, h) do { _Pragma("unroll") for (int n = 0; n < 2; ++n) _Pragma("unroll") for (int k = 0; k < 2; ++k) dst[n][k] = *(const PG8_LAS bf16x8*)(lds + PG8_SB(b, h) + boff + n * 2048 + k * 1024); } while (0)
; #define PG8_MMA(ai, bj, At, Bt) do { __builtin_amdgcn_s_setprio(1); _Pragma("unroll") for (int m = 0; m < 4; ++m) _Pragma("unroll") for (int n = 0; n < 2; ++n) _Pragma("unroll") for (int k = 0; k < 2; ++k) \
;         acc[ai][bj][m][n] = __builtin_amdgcn_mfma_f32_16x16x32_bf16(Bt[n][k], At[m][k], acc[ai][bj][m][n], 0, 0, 0); __builtin_amdgcn_s_setprio(0); } while (0)
; #define PG8_BAR __builtin_amdgcn_s_barrier()
; template <class Epi, class Sched, bool STAMP = false>
; __device__ __forceinline__ void gemm_phase(PG8_LAS unsigned char* lds, const Gemm g, const Sched& S, const Epi& E, unsigned long long* stamps) {
;     ...
;         for (int t = 0; t < nt; t += 2) {
;             const bool last = (t == nt - 2);
;             const char* a1 = cA + (size_t)(t + 1) * kstep;
;             const char* a2 = last ? nA : cA + (size_t)(t + 2) * kstep; const char* b2 = last ? nB : cB + (size_t)(t + 2) * kstep;
;             const char* a3 = a2 + kstep; const char* b3 = b2 + kstep;
;             if (last && has_next) S.a_ready(nxt);
;             PG8_LDB(B0, 0, 0); PG8_SCHED; PG8_LDA(At, 0, 0); PG8_STAGE(PG8_SA(1, 1), a1 + hstep, voffA);
;             PG8_WAIT_L(8); PG8_BAR; PG8_WAIT_L(0); PG8_MMA(0, 0, At, B0); PG8_BAR; PG8_SCHED;
;             PG8_LDB(B1, 0, 1); PG8_STAGE(PG8_SB(0, 0), b2, voffB);
;             PG8_BAR; PG8_WAIT_L(0); PG8_MMA(0, 1, At, B1); PG8_BAR;
;             PG8_LDA(At, 0, 1); PG8_STAGE(PG8_SA(0, 0), a2, voffA);
;             PG8_BAR; PG8_WAIT_L(0); PG8_MMA(1, 0, At, B0); PG8_BAR; PG8_SCHED;
;             PG8_STAGE(PG8_SB(0, 1), b2 + hstep, voffB);
;             PG8_WAIT_V(6); PG8_BAR; PG8_MMA(1, 1, At, B1); PG8_BAR;
.Lg_peel:
	s_add_i32 s93, s22, 2
	s_add_u32 s38, s0, 0x80
	s_addc_u32 s23, s1, 0
	s_add_i32 s62, 0, 0x10000
	v_add_u32_e32 v142, s62, v217
	ds_read_b128 v[130:133], v142
	ds_read_b128 v[134:137], v142 offset:1024
	ds_read_b128 v[138:141], v142 offset:2048
	ds_read_b128 v[142:145], v142 offset:3072
	s_cmp_eq_u32 s4, s22
	s_cselect_b32 s22, s90, s38
	s_cselect_b32 s23, s91, s23
	s_cselect_b32 s39, s31, s89
	s_cselect_b32 s38, s30, s88
	s_add_i32 m0, s80, 0xc000
	ds_read_b128 v[146:149], v218
	ds_read_b128 v[150:153], v218 offset:1024
	ds_read_b128 v[154:157], v218 offset:2048
	ds_read_b128 v[158:161], v218 offset:3072
	ds_read_b128 v[176:179], v218 offset:4096
	ds_read_b128 v[180:183], v218 offset:5120
	ds_read_b128 v[184:187], v218 offset:6144
	ds_read_b128 v[188:191], v218 offset:7168
	global_load_lds_dwordx4 v172, s[0:1]
	s_add_i32 m0, s80, 0xe000
	s_nop 0
	global_load_lds_dwordx4 v174, s[0:1]
	s_waitcnt lgkmcnt(8)
	s_barrier
	s_waitcnt lgkmcnt(0)
	v_mfma_f32_16x16x32_bf16 v[126:129], v[130:133], v[146:149], 0
	v_mfma_f32_16x16x32_bf16 v[122:125], v[138:141], v[146:149], 0
	v_mfma_f32_16x16x32_bf16 v[118:121], v[130:133], v[154:157], 0
	v_mfma_f32_16x16x32_bf16 v[114:117], v[138:141], v[154:157], 0
	v_mfma_f32_16x16x32_bf16 v[102:105], v[130:133], v[176:179], 0
	v_mfma_f32_16x16x32_bf16 v[98:101], v[138:141], v[176:179], 0
	v_mfma_f32_16x16x32_bf16 v[86:89], v[130:133], v[184:187], 0
	v_mfma_f32_16x16x32_bf16 v[82:85], v[138:141], v[184:187], 0
	v_mfma_f32_16x16x32_bf16 v[126:129], v[134:137], v[150:153], v[126:129]
	v_mfma_f32_16x16x32_bf16 v[122:125], v[142:145], v[150:153], v[122:125]
	v_mfma_f32_16x16x32_bf16 v[118:121], v[134:137], v[158:161], v[118:121]
	v_mfma_f32_16x16x32_bf16 v[114:117], v[142:145], v[158:161], v[114:117]
	v_mfma_f32_16x16x32_bf16 v[102:105], v[134:137], v[180:183], v[102:105]
	v_mfma_f32_16x16x32_bf16 v[98:101], v[142:145], v[180:183], v[98:101]
	v_mfma_f32_16x16x32_bf16 v[86:89], v[134:137], v[188:191], v[86:89]
	v_mfma_f32_16x16x32_bf16 v[82:85], v[142:145], v[188:191], v[82:85]
	s_barrier
	s_add_i32 s63, 0, 0x14000
	s_add_i32 s62, s62, s79
	v_add_u32_e32 v204, s63, v217
	s_add_u32 s98, s38, s10
	s_addc_u32 s99, s39, s11
	s_mov_b32 m0, s62
	ds_read_b128 v[192:195], v204
	ds_read_b128 v[196:199], v204 offset:1024
	ds_read_b128 v[200:203], v204 offset:2048
	ds_read_b128 v[204:207], v204 offset:3072
	global_load_lds_dwordx4 v164, s[38:39]
	s_add_i32 m0, s62, 0x2000
	s_nop 0
	global_load_lds_dwordx4 v170, s[38:39]
	s_barrier
	s_waitcnt lgkmcnt(0)
	v_mfma_f32_16x16x32_bf16 v[110:113], v[192:195], v[146:149], 0
	v_mfma_f32_16x16x32_bf16 v[106:109], v[200:203], v[146:149], 0
	v_mfma_f32_16x16x32_bf16 v[94:97], v[192:195], v[154:157], 0
	v_mfma_f32_16x16x32_bf16 v[90:93], v[200:203], v[154:157], 0
	v_mfma_f32_16x16x32_bf16 v[78:81], v[192:195], v[176:179], 0
	v_mfma_f32_16x16x32_bf16 v[74:77], v[200:203], v[176:179], 0
	v_mfma_f32_16x16x32_bf16 v[70:73], v[192:195], v[184:187], 0
	v_mfma_f32_16x16x32_bf16 v[66:69], v[200:203], v[184:187], 0
	v_mfma_f32_16x16x32_bf16 v[110:113], v[196:199], v[150:153], v[110:113]
	v_mfma_f32_16x16x32_bf16 v[106:109], v[204:207], v[150:153], v[106:109]
	v_mfma_f32_16x16x32_bf16 v[94:97], v[196:199], v[158:161], v[94:97]
	v_mfma_f32_16x16x32_bf16 v[90:93], v[204:207], v[158:161], v[90:93]
	v_mfma_f32_16x16x32_bf16 v[78:81], v[196:199], v[180:183], v[78:81]
	v_mfma_f32_16x16x32_bf16 v[74:77], v[204:207], v[180:183], v[74:77]
	v_mfma_f32_16x16x32_bf16 v[70:73], v[196:199], v[188:191], v[70:73]
	v_mfma_f32_16x16x32_bf16 v[66:69], v[204:207], v[188:191], v[66:69]
	s_mov_b32 m0, s80
	s_add_u32 s100, s22, s10
	s_addc_u32 s101, s23, s11
	s_barrier
	ds_read_b128 v[146:149], v218 offset:16384
	ds_read_b128 v[150:153], v218 offset:17408
	ds_read_b128 v[154:157], v218 offset:18432
	ds_read_b128 v[158:161], v218 offset:19456
	ds_read_b128 v[176:179], v218 offset:20480
	ds_read_b128 v[180:183], v218 offset:21504
	ds_read_b128 v[184:187], v218 offset:22528
	ds_read_b128 v[188:191], v218 offset:23552
	global_load_lds_dwordx4 v162, s[22:23]
	s_mov_b32 m0, s81
	s_nop 0
	global_load_lds_dwordx4 v166, s[22:23]
	s_barrier
	s_waitcnt lgkmcnt(0)
	v_mfma_f32_16x16x32_bf16 v[62:65], v[130:133], v[146:149], 0
	v_mfma_f32_16x16x32_bf16 v[58:61], v[138:141], v[146:149], 0
	v_mfma_f32_16x16x32_bf16 v[54:57], v[130:133], v[154:157], 0
	v_mfma_f32_16x16x32_bf16 v[50:53], v[138:141], v[154:157], 0
	v_mfma_f32_16x16x32_bf16 v[38:41], v[130:133], v[176:179], 0
	v_mfma_f32_16x16x32_bf16 v[34:37], v[138:141], v[176:179], 0
	v_mfma_f32_16x16x32_bf16 v[22:25], v[130:133], v[184:187], 0
	v_mfma_f32_16x16x32_bf16 v[18:21], v[138:141], v[184:187], 0
	v_mfma_f32_16x16x32_bf16 v[62:65], v[134:137], v[150:153], v[62:65]
	v_mfma_f32_16x16x32_bf16 v[58:61], v[142:145], v[150:153], v[58:61]
	v_mfma_f32_16x16x32_bf16 v[54:57], v[134:137], v[158:161], v[54:57]
	v_mfma_f32_16x16x32_bf16 v[50:53], v[142:145], v[158:161], v[50:53]
	v_mfma_f32_16x16x32_bf16 v[38:41], v[134:137], v[180:183], v[38:41]
	v_mfma_f32_16x16x32_bf16 v[34:37], v[142:145], v[180:183], v[34:37]
	v_mfma_f32_16x16x32_bf16 v[22:25], v[134:137], v[188:191], v[22:25]
	v_mfma_f32_16x16x32_bf16 v[18:21], v[142:145], v[188:191], v[18:21]
	s_barrier
	s_add_u32 s38, s38, s94
	s_addc_u32 s39, s39, 0
	s_add_i32 s62, s63, s79
	s_mov_b32 m0, s62
	global_load_lds_dwordx4 v164, s[38:39]
	s_add_i32 m0, s62, 0x2000
	s_nop 0
	global_load_lds_dwordx4 v170, s[38:39]
	s_waitcnt vmcnt(6)
	s_barrier
; #define PG8_STAGE(bufoff, gbase, voff) do { _Pragma("unroll") for (int _i = 0; _i < 2; ++_i) \
;         __builtin_amdgcn_global_load_lds((const unsigned*)((const char*)(gbase) + (voff)[_i]), (PG8_LAS unsigned*)(lds + (bufoff) + ldsw + _i * 8192), 16, 0, 0); } while (0)
; #define PG8_LDA(dst, b, h) do { _Pragma("unroll") for (int m = 0; m < 4; ++m) _Pragma("unroll") for (int k = 0; k < 2; ++k) dst[m][k] = *(const PG8_LAS bf16x8*)(lds + PG8_SA(b, h) + aoff + m * 2048 + k * 1024); } while (0)
; #define PG8_LDB(dst, b, h) do { _Pragma("unroll") for (int n = 0; n < 2; ++n) _Pragma("unroll") for (int k = 0; k < 2; ++k) dst[n][k] = *(const PG8_LAS bf16x8*)(lds + PG8_SB(b, h) + boff + n * 2048 + k * 1024); } while (0)
; #define PG8_MMA(ai, bj, At, Bt) do { __builtin_amdgcn_s_setprio(1); _Pragma("unroll") for (int m = 0; m < 4; ++m) _Pragma("unroll") for (int n = 0; n < 2; ++n) _Pragma("unroll") for (int k = 0; k < 2; ++k) \
;         acc[ai][bj][m][n] = __builtin_amdgcn_mfma_f32_16x16x32_bf16(Bt[n][k], At[m][k], acc[ai][bj][m][n], 0, 0, 0); __builtin_amdgcn_s_setprio(0); } while (0)
; #define PG8_WAIT_V(n) asm volatile("s_waitcnt vmcnt(" #n ")" ::: "memory")
; #define PG8_WAIT_L(n) asm volatile("s_waitcnt lgkmcnt(" #n ")" ::: "memory")
; #define PG8_BAR __builtin_amdgcn_s_barrier()
; #define PG8_SCHED __builtin_amdgcn_sched_barrier(0)
; template <class Epi, class Sched, bool STAMP = false>
; __device__ __forceinline__ void gemm_phase(PG8_LAS unsigned char* lds, const Gemm g, const Sched& S, const Epi& E, unsigned long long* stamps) {
;     ...
;             PG8_WAIT_V(6); PG8_BAR; PG8_MMA(1, 1, At, B1); PG8_BAR;
;             PG8_LDB(B0, 1, 0); PG8_SCHED; PG8_LDA(At, 1, 0); PG8_STAGE(PG8_SA(0, 1), a2 + hstep, voffA);
;             PG8_WAIT_L(8); PG8_BAR; PG8_WAIT_L(0); PG8_MMA(0, 0, At, B0); PG8_BAR; PG8_SCHED;
;             PG8_LDB(B1, 1, 1); PG8_STAGE(PG8_SB(1, 0), b3, voffB);
;             PG8_BAR; PG8_WAIT_L(0); PG8_MMA(0, 1, At, B1); PG8_BAR;
;             PG8_LDA(At, 1, 1); PG8_STAGE(PG8_SA(1, 0), a3, voffA);
;             PG8_BAR; PG8_WAIT_L(0); PG8_MMA(1, 0, At, B0); PG8_BAR; PG8_SCHED;
	v_mfma_f32_16x16x32_bf16 v[46:49], v[192:195], v[146:149], 0
	v_mfma_f32_16x16x32_bf16 v[42:45], v[200:203], v[146:149], 0
	v_mfma_f32_16x16x32_bf16 v[30:33], v[192:195], v[154:157], 0
	v_mfma_f32_16x16x32_bf16 v[26:29], v[200:203], v[154:157], 0
	v_mfma_f32_16x16x32_bf16 v[14:17], v[192:195], v[176:179], 0
	v_mfma_f32_16x16x32_bf16 v[10:13], v[200:203], v[176:179], 0
	v_mfma_f32_16x16x32_bf16 v[6:9], v[192:195], v[184:187], 0
	v_mfma_f32_16x16x32_bf16 v[2:5], v[200:203], v[184:187], 0
	v_mfma_f32_16x16x32_bf16 v[46:49], v[196:199], v[150:153], v[46:49]
	v_mfma_f32_16x16x32_bf16 v[42:45], v[204:207], v[150:153], v[42:45]
	v_mfma_f32_16x16x32_bf16 v[30:33], v[196:199], v[158:161], v[30:33]
	v_mfma_f32_16x16x32_bf16 v[26:29], v[204:207], v[158:161], v[26:29]
	v_mfma_f32_16x16x32_bf16 v[14:17], v[196:199], v[180:183], v[14:17]
	v_mfma_f32_16x16x32_bf16 v[10:13], v[204:207], v[180:183], v[10:13]
	v_mfma_f32_16x16x32_bf16 v[6:9], v[196:199], v[188:191], v[6:9]
	v_mfma_f32_16x16x32_bf16 v[2:5], v[204:207], v[188:191], v[2:5]
	s_add_i32 s38, 0, 0x18000
	v_add_u32_e32 v142, s38, v217
	s_barrier
	ds_read_b128 v[130:133], v142
	ds_read_b128 v[134:137], v142 offset:1024
	ds_read_b128 v[138:141], v142 offset:2048
	ds_read_b128 v[142:145], v142 offset:3072
	s_add_u32 s22, s22, s94
	s_addc_u32 s23, s23, 0
	s_mov_b32 m0, s84
	ds_read_b128 v[146:149], v218 offset:32768
	ds_read_b128 v[150:153], v218 offset:33792
	ds_read_b128 v[154:157], v218 offset:34816
	ds_read_b128 v[158:161], v218 offset:35840
	ds_read_b128 v[176:179], v218 offset:36864
	ds_read_b128 v[180:183], v218 offset:37888
	ds_read_b128 v[184:187], v218 offset:38912
	ds_read_b128 v[188:191], v218 offset:39936
	global_load_lds_dwordx4 v162, s[22:23]
	s_mov_b32 m0, s85
	s_nop 0
	global_load_lds_dwordx4 v166, s[22:23]
	s_waitcnt lgkmcnt(8)
	s_barrier
	s_waitcnt lgkmcnt(0)
	v_mfma_f32_16x16x32_bf16 v[126:129], v[130:133], v[146:149], v[126:129]
	v_mfma_f32_16x16x32_bf16 v[122:125], v[138:141], v[146:149], v[122:125]
	v_mfma_f32_16x16x32_bf16 v[118:121], v[130:133], v[154:157], v[118:121]
	v_mfma_f32_16x16x32_bf16 v[114:117], v[138:141], v[154:157], v[114:117]
	v_mfma_f32_16x16x32_bf16 v[102:105], v[130:133], v[176:179], v[102:105]
	v_mfma_f32_16x16x32_bf16 v[98:101], v[138:141], v[176:179], v[98:101]
	v_mfma_f32_16x16x32_bf16 v[86:89], v[130:133], v[184:187], v[86:89]
	v_mfma_f32_16x16x32_bf16 v[82:85], v[138:141], v[184:187], v[82:85]
	v_mfma_f32_16x16x32_bf16 v[126:129], v[134:137], v[150:153], v[126:129]
	v_mfma_f32_16x16x32_bf16 v[122:125], v[142:145], v[150:153], v[122:125]
	v_mfma_f32_16x16x32_bf16 v[118:121], v[134:137], v[158:161], v[118:121]
	v_mfma_f32_16x16x32_bf16 v[114:117], v[142:145], v[158:161], v[114:117]
	v_mfma_f32_16x16x32_bf16 v[102:105], v[134:137], v[180:183], v[102:105]
	v_mfma_f32_16x16x32_bf16 v[98:101], v[142:145], v[180:183], v[98:101]
	v_mfma_f32_16x16x32_bf16 v[86:89], v[134:137], v[188:191], v[86:89]
	v_mfma_f32_16x16x32_bf16 v[82:85], v[142:145], v[188:191], v[82:85]
	s_barrier
	s_add_i32 s22, s38, s79
	v_add_u32_e32 v204, s35, v217
	s_mov_b32 m0, s22
	ds_read_b128 v[192:195], v204
	ds_read_b128 v[196:199], v204 offset:1024
	ds_read_b128 v[200:203], v204 offset:2048
	ds_read_b128 v[204:207], v204 offset:3072
	global_load_lds_dwordx4 v164, s[98:99]
	s_add_i32 m0, s22, 0x2000
	s_nop 0
	global_load_lds_dwordx4 v170, s[98:99]
	s_add_u32 s98, s98, s94
	s_addc_u32 s99, s99, 0
	s_barrier
	s_waitcnt lgkmcnt(0)
	v_mfma_f32_16x16x32_bf16 v[110:113], v[192:195], v[146:149], v[110:113]
	v_mfma_f32_16x16x32_bf16 v[106:109], v[200:203], v[146:149], v[106:109]
	v_mfma_f32_16x16x32_bf16 v[94:97], v[192:195], v[154:157], v[94:97]
	v_mfma_f32_16x16x32_bf16 v[90:93], v[200:203], v[154:157], v[90:93]
	v_mfma_f32_16x16x32_bf16 v[78:81], v[192:195], v[176:179], v[78:81]
	v_mfma_f32_16x16x32_bf16 v[74:77], v[200:203], v[176:179], v[74:77]
	v_mfma_f32_16x16x32_bf16 v[70:73], v[192:195], v[184:187], v[70:73]
	v_mfma_f32_16x16x32_bf16 v[66:69], v[200:203], v[184:187], v[66:69]
	v_mfma_f32_16x16x32_bf16 v[110:113], v[196:199], v[150:153], v[110:113]
	v_mfma_f32_16x16x32_bf16 v[106:109], v[204:207], v[150:153], v[106:109]
	v_mfma_f32_16x16x32_bf16 v[94:97], v[196:199], v[158:161], v[94:97]
	v_mfma_f32_16x16x32_bf16 v[90:93], v[204:207], v[158:161], v[90:93]
	v_mfma_f32_16x16x32_bf16 v[78:81], v[196:199], v[180:183], v[78:81]
	v_mfma_f32_16x16x32_bf16 v[74:77], v[204:207], v[180:183], v[74:77]
	v_mfma_f32_16x16x32_bf16 v[70:73], v[196:199], v[188:191], v[70:73]
	v_mfma_f32_16x16x32_bf16 v[66:69], v[204:207], v[188:191], v[66:69]
	s_mov_b32 m0, s33
	s_barrier
	ds_read_b128 v[146:149], v218 offset:49152
	ds_read_b128 v[150:153], v218 offset:50176
	ds_read_b128 v[154:157], v218 offset:51200
	ds_read_b128 v[158:161], v218 offset:52224
	ds_read_b128 v[176:179], v218 offset:53248
	ds_read_b128 v[180:183], v218 offset:54272
	ds_read_b128 v[184:187], v218 offset:55296
	ds_read_b128 v[188:191], v218 offset:56320
	global_load_lds_dwordx4 v162, s[100:101]
	s_mov_b32 m0, s28
	s_nop 0
	global_load_lds_dwordx4 v166, s[100:101]
	s_barrier
	s_waitcnt lgkmcnt(0)
	v_mfma_f32_16x16x32_bf16 v[62:65], v[130:133], v[146:149], v[62:65]
	v_mfma_f32_16x16x32_bf16 v[58:61], v[138:141], v[146:149], v[58:61]
	v_mfma_f32_16x16x32_bf16 v[54:57], v[130:133], v[154:157], v[54:57]
	v_mfma_f32_16x16x32_bf16 v[50:53], v[138:141], v[154:157], v[50:53]
	v_mfma_f32_16x16x32_bf16 v[38:41], v[130:133], v[176:179], v[38:41]
	v_mfma_f32_16x16x32_bf16 v[34:37], v[138:141], v[176:179], v[34:37]
	v_mfma_f32_16x16x32_bf16 v[22:25], v[130:133], v[184:187], v[22:25]
	v_mfma_f32_16x16x32_bf16 v[18:21], v[138:141], v[184:187], v[18:21]
	v_mfma_f32_16x16x32_bf16 v[62:65], v[134:137], v[150:153], v[62:65]
	v_mfma_f32_16x16x32_bf16 v[58:61], v[142:145], v[150:153], v[58:61]
	v_mfma_f32_16x16x32_bf16 v[54:57], v[134:137], v[158:161], v[54:57]
	v_mfma_f32_16x16x32_bf16 v[50:53], v[142:145], v[158:161], v[50:53]
	v_mfma_f32_16x16x32_bf16 v[38:41], v[134:137], v[180:183], v[38:41]
	v_mfma_f32_16x16x32_bf16 v[34:37], v[142:145], v[180:183], v[34:37]
	v_mfma_f32_16x16x32_bf16 v[22:25], v[134:137], v[188:191], v[22:25]
	v_mfma_f32_16x16x32_bf16 v[18:21], v[142:145], v[188:191], v[18:21]
	s_barrier
; #define PG8_STAGE(bufoff, gbase, voff) do { _Pragma("unroll") for (int _i = 0; _i < 2; ++_i) \
;         __builtin_amdgcn_global_load_lds((const unsigned*)((const char*)(gbase) + (voff)[_i]), (PG8_LAS unsigned*)(lds + (bufoff) + ldsw + _i * 8192), 16, 0, 0); } while (0)
; #define PG8_LDA(dst, b, h) do { _Pragma("unroll") for (int m = 0; m < 4; ++m) _Pragma("unroll") for (int k = 0; k < 2; ++k) dst[m][k] = *(const PG8_LAS bf16x8*)(lds + PG8_SA(b, h) + aoff + m * 2048 + k * 1024); } while (0)
; #define PG8_LDB(dst, b, h) do { _Pragma("unroll") for (int n = 0; n < 2; ++n) _Pragma("unroll") for (int k = 0; k < 2; ++k) dst[n][k] = *(const PG8_LAS bf16x8*)(lds + PG8_SB(b, h) + boff + n * 2048 + k * 1024); } while (0)
; #define PG8_MMA(ai, bj, At, Bt) do { __builtin_amdgcn_s_setprio(1); _Pragma("unroll") for (int m = 0; m < 4; ++m) _Pragma("unroll") for (int n = 0; n < 2; ++n) _Pragma("unroll") for (int k = 0; k < 2; ++k) \
;         acc[ai][bj][m][n] = __builtin_amdgcn_mfma_f32_16x16x32_bf16(Bt[n][k], At[m][k], acc[ai][bj][m][n], 0, 0, 0); __builtin_amdgcn_s_setprio(0); } while (0)
; #define PG8_WAIT_V(n) asm volatile("s_waitcnt vmcnt(" #n ")" ::: "memory")
; #define PG8_WAIT_L(n) asm volatile("s_waitcnt lgkmcnt(" #n ")" ::: "memory")
; #define PG8_BAR __builtin_amdgcn_s_barrier()
; #define PG8_SCHED __builtin_amdgcn_sched_barrier(0)
; template <class Epi, class Sched, bool STAMP = false>
; __device__ __forceinline__ void gemm_phase(PG8_LAS unsigned char* lds, const Gemm g, const Sched& S, const Epi& E, unsigned long long* stamps) {
;     ...
;             PG8_LDB(B0, 0, 0); PG8_SCHED; PG8_LDA(At, 0, 0); PG8_STAGE(PG8_SA(1, 1), a1 + hstep, voffA);
;             PG8_WAIT_L(8); PG8_BAR; PG8_WAIT_L(0); PG8_MMA(0, 0, At, B0); PG8_BAR; PG8_SCHED;
;             PG8_LDB(B1, 0, 1); PG8_STAGE(PG8_SB(0, 0), b2, voffB);
;             PG8_BAR; PG8_WAIT_L(0); PG8_MMA(0, 1, At, B1); PG8_BAR;
;             PG8_LDA(At, 0, 1); PG8_STAGE(PG8_SA(0, 0), a2, voffA);
;     ...
;             PG8_STAGE(PG8_SB(1, 1), b3 + hstep, voffB);
;             PG8_WAIT_V(6); PG8_BAR; PG8_MMA(1, 1, At, B1); PG8_BAR;
	s_add_i32 s22, s35, s79
	s_mov_b32 m0, s22
	s_nop 0
	global_load_lds_dwordx4 v164, s[98:99]
	s_add_i32 m0, s22, 0x2000
	s_nop 0
	global_load_lds_dwordx4 v170, s[98:99]
	s_waitcnt vmcnt(6)
	s_barrier
	v_mfma_f32_16x16x32_bf16 v[46:49], v[192:195], v[146:149], v[46:49]
	v_mfma_f32_16x16x32_bf16 v[42:45], v[200:203], v[146:149], v[42:45]
	v_mfma_f32_16x16x32_bf16 v[30:33], v[192:195], v[154:157], v[30:33]
	v_mfma_f32_16x16x32_bf16 v[26:29], v[200:203], v[154:157], v[26:29]
	v_mfma_f32_16x16x32_bf16 v[14:17], v[192:195], v[176:179], v[14:17]
	v_mfma_f32_16x16x32_bf16 v[10:13], v[200:203], v[176:179], v[10:13]
	v_mfma_f32_16x16x32_bf16 v[6:9], v[192:195], v[184:187], v[6:9]
	v_mfma_f32_16x16x32_bf16 v[2:5], v[200:203], v[184:187], v[2:5]
	v_mfma_f32_16x16x32_bf16 v[46:49], v[196:199], v[150:153], v[46:49]
	v_mfma_f32_16x16x32_bf16 v[42:45], v[204:207], v[150:153], v[42:45]
	v_mfma_f32_16x16x32_bf16 v[30:33], v[196:199], v[158:161], v[30:33]
	v_mfma_f32_16x16x32_bf16 v[26:29], v[204:207], v[158:161], v[26:29]
	v_mfma_f32_16x16x32_bf16 v[14:17], v[196:199], v[180:183], v[14:17]
	v_mfma_f32_16x16x32_bf16 v[10:13], v[204:207], v[180:183], v[10:13]
	v_mfma_f32_16x16x32_bf16 v[6:9], v[196:199], v[188:191], v[6:9]
	v_mfma_f32_16x16x32_bf16 v[2:5], v[204:207], v[188:191], v[2:5]
	s_add_u32 s0, s0, 0x100
	s_addc_u32 s1, s1, 0
	s_add_u32 s88, s88, 0x100
	s_addc_u32 s89, s89, 0
	s_cmp_ge_u32 s93, s26
	s_mov_b32 s22, s93
	s_barrier
	s_cbranch_scc0 .LBB0_745
	s_branch .Lg_epi
.LBB0_745:
	s_add_i32 s93, s22, 2
	s_add_u32 s38, s0, 0x80
	s_addc_u32 s23, s1, 0
	s_add_i32 s62, 0, 0x10000
	v_add_u32_e32 v142, s62, v217
	ds_read_b128 v[130:133], v142
	ds_read_b128 v[134:137], v142 offset:1024
	ds_read_b128 v[138:141], v142 offset:2048
	ds_read_b128 v[142:145], v142 offset:3072
	s_cmp_eq_u32 s4, s22
	s_cselect_b32 s22, s90, s38
	s_cselect_b32 s23, s91, s23
	s_cselect_b32 s39, s31, s89
	s_cselect_b32 s38, s30, s88
	s_add_i32 m0, s80, 0xc000
	ds_read_b128 v[146:149], v218
	ds_read_b128 v[150:153], v218 offset:1024
	ds_read_b128 v[154:157], v218 offset:2048
	ds_read_b128 v[158:161], v218 offset:3072
	ds_read_b128 v[176:179], v218 offset:4096
	ds_read_b128 v[180:183], v218 offset:5120
	ds_read_b128 v[184:187], v218 offset:6144
	ds_read_b128 v[188:191], v218 offset:7168
	global_load_lds_dwordx4 v172, s[0:1]
	s_add_i32 m0, s80, 0xe000
	s_nop 0
	global_load_lds_dwordx4 v174, s[0:1]
	s_waitcnt lgkmcnt(8)
	s_barrier
	s_waitcnt lgkmcnt(0)
	v_mfma_f32_16x16x32_bf16 v[126:129], v[130:133], v[146:149], v[126:129]
	v_mfma_f32_16x16x32_bf16 v[122:125], v[138:141], v[146:149], v[122:125]
	v_mfma_f32_16x16x32_bf16 v[118:121], v[130:133], v[154:157], v[118:121]
	v_mfma_f32_16x16x32_bf16 v[114:117], v[138:141], v[154:157], v[114:117]
	v_mfma_f32_16x16x32_bf16 v[102:105], v[130:133], v[176:179], v[102:105]
	v_mfma_f32_16x16x32_bf16 v[98:101], v[138:141], v[176:179], v[98:101]
	v_mfma_f32_16x16x32_bf16 v[86:89], v[130:133], v[184:187], v[86:89]
	v_mfma_f32_16x16x32_bf16 v[82:85], v[138:141], v[184:187], v[82:85]
	v_mfma_f32_16x16x32_bf16 v[126:129], v[134:137], v[150:153], v[126:129]
	v_mfma_f32_16x16x32_bf16 v[122:125], v[142:145], v[150:153], v[122:125]
	v_mfma_f32_16x16x32_bf16 v[118:121], v[134:137], v[158:161], v[118:121]
	v_mfma_f32_16x16x32_bf16 v[114:117], v[142:145], v[158:161], v[114:117]
	v_mfma_f32_16x16x32_bf16 v[102:105], v[134:137], v[180:183], v[102:105]
	v_mfma_f32_16x16x32_bf16 v[98:101], v[142:145], v[180:183], v[98:101]
	v_mfma_f32_16x16x32_bf16 v[86:89], v[134:137], v[188:191], v[86:89]
	v_mfma_f32_16x16x32_bf16 v[82:85], v[142:145], v[188:191], v[82:85]
	s_barrier
	s_add_i32 s63, 0, 0x14000
	s_add_i32 s62, s62, s79
	v_add_u32_e32 v204, s63, v217
	s_add_u32 s98, s38, s10
	s_addc_u32 s99, s39, s11
	s_mov_b32 m0, s62
	ds_read_b128 v[192:195], v204
	ds_read_b128 v[196:199], v204 offset:1024
	ds_read_b128 v[200:203], v204 offset:2048
	ds_read_b128 v[204:207], v204 offset:3072
	global_load_lds_dwordx4 v164, s[38:39]
	s_add_i32 m0, s62, 0x2000
	s_nop 0
	global_load_lds_dwordx4 v170, s[38:39]
	s_barrier
	s_waitcnt lgkmcnt(0)
	v_mfma_f32_16x16x32_bf16 v[110:113], v[192:195], v[146:149], v[110:113]
	v_mfma_f32_16x16x32_bf16 v[106:109], v[200:203], v[146:149], v[106:109]
	v_mfma_f32_16x16x32_bf16 v[94:97], v[192:195], v[154:157], v[94:97]
	v_mfma_f32_16x16x32_bf16 v[90:93], v[200:203], v[154:157], v[90:93]
	v_mfma_f32_16x16x32_bf16 v[78:81], v[192:195], v[176:179], v[78:81]
	v_mfma_f32_16x16x32_bf16 v[74:77], v[200:203], v[176:179], v[74:77]
	v_mfma_f32_16x16x32_bf16 v[70:73], v[192:195], v[184:187], v[70:73]
	v_mfma_f32_16x16x32_bf16 v[66:69], v[200:203], v[184:187], v[66:69]
	v_mfma_f32_16x16x32_bf16 v[110:113], v[196:199], v[150:153], v[110:113]
	v_mfma_f32_16x16x32_bf16 v[106:109], v[204:207], v[150:153], v[106:109]
	v_mfma_f32_16x16x32_bf16 v[94:97], v[196:199], v[158:161], v[94:97]
	v_mfma_f32_16x16x32_bf16 v[90:93], v[204:207], v[158:161], v[90:93]
	v_mfma_f32_16x16x32_bf16 v[78:81], v[196:199], v[180:183], v[78:81]
	v_mfma_f32_16x16x32_bf16 v[74:77], v[204:207], v[180:183], v[74:77]
	v_mfma_f32_16x16x32_bf16 v[70:73], v[196:199], v[188:191], v[70:73]
	v_mfma_f32_16x16x32_bf16 v[66:69], v[204:207], v[188:191], v[66:69]
	s_mov_b32 m0, s80
	s_add_u32 s100, s22, s10
	s_addc_u32 s101, s23, s11
	s_barrier
	ds_read_b128 v[146:149], v218 offset:16384
	ds_read_b128 v[150:153], v218 offset:17408
	ds_read_b128 v[154:157], v218 offset:18432
	ds_read_b128 v[158:161], v218 offset:19456
	ds_read_b128 v[176:179], v218 offset:20480
	ds_read_b128 v[180:183], v218 offset:21504
	ds_read_b128 v[184:187], v218 offset:22528
	ds_read_b128 v[188:191], v218 offset:23552
	global_load_lds_dwordx4 v162, s[22:23]
	s_mov_b32 m0, s81
	s_nop 0
	global_load_lds_dwordx4 v166, s[22:23]
	s_barrier
; #define PG8_STAGE(bufoff, gbase, voff) do { _Pragma("unroll") for (int _i = 0; _i < 2; ++_i) \
;         __builtin_amdgcn_global_load_lds((const unsigned*)((const char*)(gbase) + (voff)[_i]), (PG8_LAS unsigned*)(lds + (bufoff) + ldsw + _i * 8192), 16, 0, 0); } while (0)
; #define PG8_LDA(dst, b, h) do { _Pragma("unroll") for (int m = 0; m < 4; ++m) _Pragma("unroll") for (int k = 0; k < 2; ++k) dst[m][k] = *(const PG8_LAS bf16x8*)(lds + PG8_SA(b, h) + aoff + m * 2048 + k * 1024); } while (0)
; #define PG8_LDB(dst, b, h) do { _Pragma("unroll") for (int n = 0; n < 2; ++n) _Pragma("unroll") for (int k = 0; k < 2; ++k) dst[n][k] = *(const PG8_LAS bf16x8*)(lds + PG8_SB(b, h) + boff + n * 2048 + k * 1024); } while (0)
; #define PG8_MMA(ai, bj, At, Bt) do { __builtin_amdgcn_s_setprio(1); _Pragma("unroll") for (int m = 0; m < 4; ++m) _Pragma("unroll") for (int n = 0; n < 2; ++n) _Pragma("unroll") for (int k = 0; k < 2; ++k) \
;         acc[ai][bj][m][n] = __builtin_amdgcn_mfma_f32_16x16x32_bf16(Bt[n][k], At[m][k], acc[ai][bj][m][n], 0, 0, 0); __builtin_amdgcn_s_setprio(0); } while (0)
; #define PG8_WAIT_V(n) asm volatile("s_waitcnt vmcnt(" #n ")" ::: "memory")
; #define PG8_WAIT_L(n) asm volatile("s_waitcnt lgkmcnt(" #n ")" ::: "memory")
; #define PG8_BAR __builtin_amdgcn_s_barrier()
; #define PG8_SCHED __builtin_amdgcn_sched_barrier(0)
; template <class Epi, class Sched, bool STAMP = false>
; __device__ __forceinline__ void gemm_phase(PG8_LAS unsigned char* lds, const Gemm g, const Sched& S, const Epi& E, unsigned long long* stamps) {
;     ...
;             PG8_BAR; PG8_WAIT_L(0); PG8_MMA(1, 0, At, B0); PG8_BAR; PG8_SCHED;
;             PG8_STAGE(PG8_SB(0, 1), b2 + hstep, voffB);
;             PG8_WAIT_V(6); PG8_BAR; PG8_MMA(1, 1, At, B1); PG8_BAR;
;             PG8_LDB(B0, 1, 0); PG8_SCHED; PG8_LDA(At, 1, 0); PG8_STAGE(PG8_SA(0, 1), a2 + hstep, voffA);
;             PG8_WAIT_L(8); PG8_BAR; PG8_WAIT_L(0); PG8_MMA(0, 0, At, B0); PG8_BAR; PG8_SCHED;
	s_waitcnt lgkmcnt(0)
	v_mfma_f32_16x16x32_bf16 v[62:65], v[130:133], v[146:149], v[62:65]
	v_mfma_f32_16x16x32_bf16 v[58:61], v[138:141], v[146:149], v[58:61]
	v_mfma_f32_16x16x32_bf16 v[54:57], v[130:133], v[154:157], v[54:57]
	v_mfma_f32_16x16x32_bf16 v[50:53], v[138:141], v[154:157], v[50:53]
	v_mfma_f32_16x16x32_bf16 v[38:41], v[130:133], v[176:179], v[38:41]
	v_mfma_f32_16x16x32_bf16 v[34:37], v[138:141], v[176:179], v[34:37]
	v_mfma_f32_16x16x32_bf16 v[22:25], v[130:133], v[184:187], v[22:25]
	v_mfma_f32_16x16x32_bf16 v[18:21], v[138:141], v[184:187], v[18:21]
	v_mfma_f32_16x16x32_bf16 v[62:65], v[134:137], v[150:153], v[62:65]
	v_mfma_f32_16x16x32_bf16 v[58:61], v[142:145], v[150:153], v[58:61]
	v_mfma_f32_16x16x32_bf16 v[54:57], v[134:137], v[158:161], v[54:57]
	v_mfma_f32_16x16x32_bf16 v[50:53], v[142:145], v[158:161], v[50:53]
	v_mfma_f32_16x16x32_bf16 v[38:41], v[134:137], v[180:183], v[38:41]
	v_mfma_f32_16x16x32_bf16 v[34:37], v[142:145], v[180:183], v[34:37]
	v_mfma_f32_16x16x32_bf16 v[22:25], v[134:137], v[188:191], v[22:25]
	v_mfma_f32_16x16x32_bf16 v[18:21], v[142:145], v[188:191], v[18:21]
	s_barrier
	s_add_u32 s38, s38, s94
	s_addc_u32 s39, s39, 0
	s_add_i32 s62, s63, s79
	s_mov_b32 m0, s62
	global_load_lds_dwordx4 v164, s[38:39]
	s_add_i32 m0, s62, 0x2000
	s_nop 0
	global_load_lds_dwordx4 v170, s[38:39]
	s_waitcnt vmcnt(6)
	s_barrier
	v_mfma_f32_16x16x32_bf16 v[46:49], v[192:195], v[146:149], v[46:49]
	v_mfma_f32_16x16x32_bf16 v[42:45], v[200:203], v[146:149], v[42:45]
	v_mfma_f32_16x16x32_bf16 v[30:33], v[192:195], v[154:157], v[30:33]
	v_mfma_f32_16x16x32_bf16 v[26:29], v[200:203], v[154:157], v[26:29]
	v_mfma_f32_16x16x32_bf16 v[14:17], v[192:195], v[176:179], v[14:17]
	v_mfma_f32_16x16x32_bf16 v[10:13], v[200:203], v[176:179], v[10:13]
	v_mfma_f32_16x16x32_bf16 v[6:9], v[192:195], v[184:187], v[6:9]
	v_mfma_f32_16x16x32_bf16 v[2:5], v[200:203], v[184:187], v[2:5]
	v_mfma_f32_16x16x32_bf16 v[46:49], v[196:199], v[150:153], v[46:49]
	v_mfma_f32_16x16x32_bf16 v[42:45], v[204:207], v[150:153], v[42:45]
	v_mfma_f32_16x16x32_bf16 v[30:33], v[196:199], v[158:161], v[30:33]
	v_mfma_f32_16x16x32_bf16 v[26:29], v[204:207], v[158:161], v[26:29]
	v_mfma_f32_16x16x32_bf16 v[14:17], v[196:199], v[180:183], v[14:17]
	v_mfma_f32_16x16x32_bf16 v[10:13], v[204:207], v[180:183], v[10:13]
	v_mfma_f32_16x16x32_bf16 v[6:9], v[196:199], v[188:191], v[6:9]
	v_mfma_f32_16x16x32_bf16 v[2:5], v[204:207], v[188:191], v[2:5]
	s_add_i32 s38, 0, 0x18000
	v_add_u32_e32 v142, s38, v217
	s_barrier
	ds_read_b128 v[130:133], v142
	ds_read_b128 v[134:137], v142 offset:1024
	ds_read_b128 v[138:141], v142 offset:2048
	ds_read_b128 v[142:145], v142 offset:3072
	s_add_u32 s22, s22, s94
	s_addc_u32 s23, s23, 0
	s_mov_b32 m0, s84
	ds_read_b128 v[146:149], v218 offset:32768
	ds_read_b128 v[150:153], v218 offset:33792
	ds_read_b128 v[154:157], v218 offset:34816
	ds_read_b128 v[158:161], v218 offset:35840
	ds_read_b128 v[176:179], v218 offset:36864
	ds_read_b128 v[180:183], v218 offset:37888
	ds_read_b128 v[184:187], v218 offset:38912
	ds_read_b128 v[188:191], v218 offset:39936
	global_load_lds_dwordx4 v162, s[22:23]
	s_mov_b32 m0, s85
	s_nop 0
	global_load_lds_dwordx4 v166, s[22:23]
	s_waitcnt lgkmcnt(8)
	s_barrier
	s_waitcnt lgkmcnt(0)
	v_mfma_f32_16x16x32_bf16 v[126:129], v[130:133], v[146:149], v[126:129]
	v_mfma_f32_16x16x32_bf16 v[122:125], v[138:141], v[146:149], v[122:125]
	v_mfma_f32_16x16x32_bf16 v[118:121], v[130:133], v[154:157], v[118:121]
	v_mfma_f32_16x16x32_bf16 v[114:117], v[138:141], v[154:157], v[114:117]
	v_mfma_f32_16x16x32_bf16 v[102:105], v[130:133], v[176:179], v[102:105]
	v_mfma_f32_16x16x32_bf16 v[98:101], v[138:141], v[176:179], v[98:101]
	v_mfma_f32_16x16x32_bf16 v[86:89], v[130:133], v[184:187], v[86:89]
	v_mfma_f32_16x16x32_bf16 v[82:85], v[138:141], v[184:187], v[82:85]
	v_mfma_f32_16x16x32_bf16 v[126:129], v[134:137], v[150:153], v[126:129]
	v_mfma_f32_16x16x32_bf16 v[122:125], v[142:145], v[150:153], v[122:125]
	v_mfma_f32_16x16x32_bf16 v[118:121], v[134:137], v[158:161], v[118:121]
	v_mfma_f32_16x16x32_bf16 v[114:117], v[142:145], v[158:161], v[114:117]
	v_mfma_f32_16x16x32_bf16 v[102:105], v[134:137], v[180:183], v[102:105]
	v_mfma_f32_16x16x32_bf16 v[98:101], v[142:145], v[180:183], v[98:101]
	v_mfma_f32_16x16x32_bf16 v[86:89], v[134:137], v[188:191], v[86:89]
	v_mfma_f32_16x16x32_bf16 v[82:85], v[142:145], v[188:191], v[82:85]
	s_barrier
; #define PG8_STAGE(bufoff, gbase, voff) do { _Pragma("unroll") for (int _i = 0; _i < 2; ++_i) \
;         __builtin_amdgcn_global_load_lds((const unsigned*)((const char*)(gbase) + (voff)[_i]), (PG8_LAS unsigned*)(lds + (bufoff) + ldsw + _i * 8192), 16, 0, 0); } while (0)
; #define PG8_LDA(dst, b, h) do { _Pragma("unroll") for (int m = 0; m < 4; ++m) _Pragma("unroll") for (int k = 0; k < 2; ++k) dst[m][k] = *(const PG8_LAS bf16x8*)(lds + PG8_SA(b, h) + aoff + m * 2048 + k * 1024); } while (0)
; #define PG8_LDB(dst, b, h) do { _Pragma("unroll") for (int n = 0; n < 2; ++n) _Pragma("unroll") for (int k = 0; k < 2; ++k) dst[n][k] = *(const PG8_LAS bf16x8*)(lds + PG8_SB(b, h) + boff + n * 2048 + k * 1024); } while (0)
; #define PG8_MMA(ai, bj, At, Bt) do { __builtin_amdgcn_s_setprio(1); _Pragma("unroll") for (int m = 0; m < 4; ++m) _Pragma("unroll") for (int n = 0; n < 2; ++n) _Pragma("unroll") for (int k = 0; k < 2; ++k) \
;         acc[ai][bj][m][n] = __builtin_amdgcn_mfma_f32_16x16x32_bf16(Bt[n][k], At[m][k], acc[ai][bj][m][n], 0, 0, 0); __builtin_amdgcn_s_setprio(0); } while (0)
; #define PG8_WAIT_V(n) asm volatile("s_waitcnt vmcnt(" #n ")" ::: "memory")
; #define PG8_WAIT_L(n) asm volatile("s_waitcnt lgkmcnt(" #n ")" ::: "memory")
; #define PG8_BAR __builtin_amdgcn_s_barrier()
; #define PG8_SCHED __builtin_amdgcn_sched_barrier(0)
; template <class Epi, class Sched, bool STAMP = false>
; __device__ __forceinline__ void gemm_phase(PG8_LAS unsigned char* lds, const Gemm g, const Sched& S, const Epi& E, unsigned long long* stamps) {
;     ...
;             PG8_LDB(B1, 1, 1); PG8_STAGE(PG8_SB(1, 0), b3, voffB);
;             PG8_BAR; PG8_WAIT_L(0); PG8_MMA(0, 1, At, B1); PG8_BAR;
;             PG8_LDA(At, 1, 1); PG8_STAGE(PG8_SA(1, 0), a3, voffA);
;             PG8_BAR; PG8_WAIT_L(0); PG8_MMA(1, 0, At, B0); PG8_BAR; PG8_SCHED;
;             PG8_STAGE(PG8_SB(1, 1), b3 + hstep, voffB);
;             PG8_WAIT_V(6); PG8_BAR; PG8_MMA(1, 1, At, B1); PG8_BAR;
;         }
	s_add_i32 s22, s38, s79
	v_add_u32_e32 v204, s35, v217
	s_mov_b32 m0, s22
	ds_read_b128 v[192:195], v204
	ds_read_b128 v[196:199], v204 offset:1024
	ds_read_b128 v[200:203], v204 offset:2048
	ds_read_b128 v[204:207], v204 offset:3072
	global_load_lds_dwordx4 v164, s[98:99]
	s_add_i32 m0, s22, 0x2000
	s_nop 0
	global_load_lds_dwordx4 v170, s[98:99]
	s_add_u32 s98, s98, s94
	s_addc_u32 s99, s99, 0
	s_barrier
	s_waitcnt lgkmcnt(0)
	v_mfma_f32_16x16x32_bf16 v[110:113], v[192:195], v[146:149], v[110:113]
	v_mfma_f32_16x16x32_bf16 v[106:109], v[200:203], v[146:149], v[106:109]
	v_mfma_f32_16x16x32_bf16 v[94:97], v[192:195], v[154:157], v[94:97]
	v_mfma_f32_16x16x32_bf16 v[90:93], v[200:203], v[154:157], v[90:93]
	v_mfma_f32_16x16x32_bf16 v[78:81], v[192:195], v[176:179], v[78:81]
	v_mfma_f32_16x16x32_bf16 v[74:77], v[200:203], v[176:179], v[74:77]
	v_mfma_f32_16x16x32_bf16 v[70:73], v[192:195], v[184:187], v[70:73]
	v_mfma_f32_16x16x32_bf16 v[66:69], v[200:203], v[184:187], v[66:69]
	v_mfma_f32_16x16x32_bf16 v[110:113], v[196:199], v[150:153], v[110:113]
	v_mfma_f32_16x16x32_bf16 v[106:109], v[204:207], v[150:153], v[106:109]
	v_mfma_f32_16x16x32_bf16 v[94:97], v[196:199], v[158:161], v[94:97]
	v_mfma_f32_16x16x32_bf16 v[90:93], v[204:207], v[158:161], v[90:93]
	v_mfma_f32_16x16x32_bf16 v[78:81], v[196:199], v[180:183], v[78:81]
	v_mfma_f32_16x16x32_bf16 v[74:77], v[204:207], v[180:183], v[74:77]
	v_mfma_f32_16x16x32_bf16 v[70:73], v[196:199], v[188:191], v[70:73]
	v_mfma_f32_16x16x32_bf16 v[66:69], v[204:207], v[188:191], v[66:69]
	s_mov_b32 m0, s33
	s_barrier
	ds_read_b128 v[146:149], v218 offset:49152
	ds_read_b128 v[150:153], v218 offset:50176
	ds_read_b128 v[154:157], v218 offset:51200
	ds_read_b128 v[158:161], v218 offset:52224
	ds_read_b128 v[176:179], v218 offset:53248
	ds_read_b128 v[180:183], v218 offset:54272
	ds_read_b128 v[184:187], v218 offset:55296
	ds_read_b128 v[188:191], v218 offset:56320
	global_load_lds_dwordx4 v162, s[100:101]
	s_mov_b32 m0, s28
	s_nop 0
	global_load_lds_dwordx4 v166, s[100:101]
	s_barrier
	s_waitcnt lgkmcnt(0)
	v_mfma_f32_16x16x32_bf16 v[62:65], v[130:133], v[146:149], v[62:65]
	v_mfma_f32_16x16x32_bf16 v[58:61], v[138:141], v[146:149], v[58:61]
	v_mfma_f32_16x16x32_bf16 v[54:57], v[130:133], v[154:157], v[54:57]
	v_mfma_f32_16x16x32_bf16 v[50:53], v[138:141], v[154:157], v[50:53]
	v_mfma_f32_16x16x32_bf16 v[38:41], v[130:133], v[176:179], v[38:41]
	v_mfma_f32_16x16x32_bf16 v[34:37], v[138:141], v[176:179], v[34:37]
	v_mfma_f32_16x16x32_bf16 v[22:25], v[130:133], v[184:187], v[22:25]
	v_mfma_f32_16x16x32_bf16 v[18:21], v[138:141], v[184:187], v[18:21]
	v_mfma_f32_16x16x32_bf16 v[62:65], v[134:137], v[150:153], v[62:65]
	v_mfma_f32_16x16x32_bf16 v[58:61], v[142:145], v[150:153], v[58:61]
	v_mfma_f32_16x16x32_bf16 v[54:57], v[134:137], v[158:161], v[54:57]
	v_mfma_f32_16x16x32_bf16 v[50:53], v[142:145], v[158:161], v[50:53]
	v_mfma_f32_16x16x32_bf16 v[38:41], v[134:137], v[180:183], v[38:41]
	v_mfma_f32_16x16x32_bf16 v[34:37], v[142:145], v[180:183], v[34:37]
	v_mfma_f32_16x16x32_bf16 v[22:25], v[134:137], v[188:191], v[22:25]
	v_mfma_f32_16x16x32_bf16 v[18:21], v[142:145], v[188:191], v[18:21]
	s_barrier
	s_add_i32 s22, s35, s79
	s_mov_b32 m0, s22
	s_nop 0
	global_load_lds_dwordx4 v164, s[98:99]
	s_add_i32 m0, s22, 0x2000
	s_nop 0
	global_load_lds_dwordx4 v170, s[98:99]
	s_waitcnt vmcnt(6)
	s_barrier
	v_mfma_f32_16x16x32_bf16 v[46:49], v[192:195], v[146:149], v[46:49]
	v_mfma_f32_16x16x32_bf16 v[42:45], v[200:203], v[146:149], v[42:45]
	v_mfma_f32_16x16x32_bf16 v[30:33], v[192:195], v[154:157], v[30:33]
	v_mfma_f32_16x16x32_bf16 v[26:29], v[200:203], v[154:157], v[26:29]
	v_mfma_f32_16x16x32_bf16 v[14:17], v[192:195], v[176:179], v[14:17]
	v_mfma_f32_16x16x32_bf16 v[10:13], v[200:203], v[176:179], v[10:13]
	v_mfma_f32_16x16x32_bf16 v[6:9], v[192:195], v[184:187], v[6:9]
	v_mfma_f32_16x16x32_bf16 v[2:5], v[200:203], v[184:187], v[2:5]
	v_mfma_f32_16x16x32_bf16 v[46:49], v[196:199], v[150:153], v[46:49]
	v_mfma_f32_16x16x32_bf16 v[42:45], v[204:207], v[150:153], v[42:45]
	v_mfma_f32_16x16x32_bf16 v[30:33], v[196:199], v[158:161], v[30:33]
	v_mfma_f32_16x16x32_bf16 v[26:29], v[204:207], v[158:161], v[26:29]
	v_mfma_f32_16x16x32_bf16 v[14:17], v[196:199], v[180:183], v[14:17]
	v_mfma_f32_16x16x32_bf16 v[10:13], v[204:207], v[180:183], v[10:13]
	v_mfma_f32_16x16x32_bf16 v[6:9], v[196:199], v[188:191], v[6:9]
	v_mfma_f32_16x16x32_bf16 v[2:5], v[204:207], v[188:191], v[2:5]
	s_add_u32 s0, s0, 0x100
	s_addc_u32 s1, s1, 0
	s_add_u32 s88, s88, 0x100
	s_addc_u32 s89, s89, 0
	s_cmp_ge_u32 s93, s26
	s_mov_b32 s22, s93
	s_barrier
	s_cbranch_scc0 .LBB0_745
